# n3 P.V fragments read directly into MFMA operand quads (48 v_mov per tile removed) and packed v_pk_mul_f32 O-rescale split into scalar v_mul_f32
# speedup vs baseline: 1.0676x; 1.0167x over previous
.LBB0_70:
	v_cmp_neq_f32_e32 vcc, 1.0, v0
	v_cmp_neq_f32_e64 s[0:1], 1.0, v2
	s_or_b64 vcc, vcc, s[0:1]
	v_cvt_pk_bf16_f32 v72, v94, v95
	v_cvt_pk_bf16_f32 v73, v96, v97
	v_cvt_pk_bf16_f32 v74, v98, v99
	v_cvt_pk_bf16_f32 v75, v217, v218
	v_cvt_pk_bf16_f32 v68, v219, v220
	v_cvt_pk_bf16_f32 v69, v221, v222
	v_cvt_pk_bf16_f32 v70, v223, v224
	v_cvt_pk_bf16_f32 v71, v225, v226
	s_cbranch_vccz .LBB0_72
	v_mul_f32_e32 v66, v66, v0
	v_mul_f32_e32 v67, v67, v0
	v_mul_f32_e32 v64, v64, v0
	v_mul_f32_e32 v65, v65, v0
	v_mul_f32_e32 v62, v62, v0
	v_mul_f32_e32 v63, v63, v0
	v_mul_f32_e32 v60, v60, v0
	v_mul_f32_e32 v61, v61, v0
	v_mul_f32_e32 v58, v58, v0
	v_mul_f32_e32 v59, v59, v0
	v_mul_f32_e32 v56, v56, v0
	v_mul_f32_e32 v57, v57, v0
	v_mul_f32_e32 v54, v54, v0
	v_mul_f32_e32 v55, v55, v0
	v_mul_f32_e32 v52, v52, v0
	v_mul_f32_e32 v53, v53, v0
	v_mul_f32_e32 v50, v50, v0
	v_mul_f32_e32 v51, v51, v0
	v_mul_f32_e32 v48, v48, v0
	v_mul_f32_e32 v49, v49, v0
	v_mul_f32_e32 v46, v46, v0
	v_mul_f32_e32 v47, v47, v0
	v_mul_f32_e32 v44, v44, v0
	v_mul_f32_e32 v45, v45, v0
	v_mul_f32_e32 v42, v42, v0
	v_mul_f32_e32 v43, v43, v0
	v_mul_f32_e32 v40, v40, v0
	v_mul_f32_e32 v41, v41, v0
	v_mul_f32_e32 v38, v38, v0
	v_mul_f32_e32 v39, v39, v0
	v_mul_f32_e32 v36, v36, v0
	v_mul_f32_e32 v37, v37, v0
	v_mul_f32_e32 v34, v34, v2
	v_mul_f32_e32 v35, v35, v2
	v_mul_f32_e32 v32, v32, v2
	v_mul_f32_e32 v33, v33, v2
	v_mul_f32_e32 v30, v30, v2
	v_mul_f32_e32 v31, v31, v2
	v_mul_f32_e32 v28, v28, v2
	v_mul_f32_e32 v29, v29, v2
	v_mul_f32_e32 v26, v26, v2
	v_mul_f32_e32 v27, v27, v2
	v_mul_f32_e32 v24, v24, v2
	v_mul_f32_e32 v25, v25, v2
	v_mul_f32_e32 v22, v22, v2
	v_mul_f32_e32 v23, v23, v2
	v_mul_f32_e32 v20, v20, v2
	v_mul_f32_e32 v21, v21, v2
	v_mul_f32_e32 v18, v18, v2
	v_mul_f32_e32 v19, v19, v2
	v_mul_f32_e32 v16, v16, v2
	v_mul_f32_e32 v17, v17, v2
	v_mul_f32_e32 v14, v14, v2
	v_mul_f32_e32 v15, v15, v2
	v_mul_f32_e32 v12, v12, v2
	v_mul_f32_e32 v13, v13, v2
	v_mul_f32_e32 v10, v10, v2
	v_mul_f32_e32 v11, v11, v2
	v_mul_f32_e32 v8, v8, v2
	v_mul_f32_e32 v9, v9, v2
	v_mul_f32_e32 v6, v6, v2
	v_mul_f32_e32 v7, v7, v2
	v_mul_f32_e32 v4, v4, v2
	v_mul_f32_e32 v5, v5, v2
.LBB0_72:
	v_add3_u32 v98, s56, v155, v154
	v_add3_u32 v99, s56, v156, v154
	ds_read_b64 v[220:221], v98 offset:32768
	ds_read_b64 v[222:223], v99 offset:32768
	ds_read_b64 v[224:225], v98 offset:34816
	ds_read_b64 v[226:227], v99 offset:34816
	ds_read_b64 v[228:229], v98 offset:36864
	ds_read_b64 v[230:231], v99 offset:36864
	ds_read_b64 v[232:233], v98 offset:38912
	ds_read_b64 v[234:235], v99 offset:38912
	ds_read_b64 v[236:237], v98 offset:40960
	ds_read_b64 v[238:239], v99 offset:40960
	ds_read_b64 v[240:241], v98 offset:43008
	ds_read_b64 v[242:243], v99 offset:43008
	ds_read_b64 v[244:245], v98 offset:45056
	ds_read_b64 v[246:247], v99 offset:45056
	ds_read_b64 v[248:249], v98 offset:47104
	ds_read_b64 v[250:251], v99 offset:47104
	v_add3_u32 v76, s56, v157, v154
	v_add3_u32 v77, s56, v158, v154
	v_fmac_f32_e32 v93, v212, v2
	v_fmac_f32_e32 v216, v213, v0
	v_mov_b32_e32 v213, v216
	v_mov_b32_e32 v212, v93
	v_mov_b32_e32 v217, v3
	v_mov_b32_e32 v215, v92
	s_waitcnt lgkmcnt(14)
	v_mfma_f32_16x16x32_bf16 v[64:67], v[220:223], v[88:91], v[64:67]
	v_mfma_f32_16x16x32_bf16 v[32:35], v[220:223], v[72:75], v[32:35]
	ds_read_b64 v[220:221], v76 offset:32768
	ds_read_b64 v[222:223], v77 offset:32768
	s_waitcnt lgkmcnt(14)
	v_mfma_f32_16x16x32_bf16 v[60:63], v[224:227], v[88:91], v[60:63]
	v_mfma_f32_16x16x32_bf16 v[28:31], v[224:227], v[72:75], v[28:31]
	ds_read_b64 v[224:225], v76 offset:34816
	ds_read_b64 v[226:227], v77 offset:34816
	s_waitcnt lgkmcnt(14)
	v_mfma_f32_16x16x32_bf16 v[56:59], v[228:231], v[88:91], v[56:59]
	v_mfma_f32_16x16x32_bf16 v[24:27], v[228:231], v[72:75], v[24:27]
	ds_read_b64 v[228:229], v76 offset:36864
	ds_read_b64 v[230:231], v77 offset:36864
	s_waitcnt lgkmcnt(14)
	v_mfma_f32_16x16x32_bf16 v[52:55], v[232:235], v[88:91], v[52:55]
	v_mfma_f32_16x16x32_bf16 v[20:23], v[232:235], v[72:75], v[20:23]
	ds_read_b64 v[232:233], v76 offset:38912
	ds_read_b64 v[234:235], v77 offset:38912
	s_waitcnt lgkmcnt(14)
	v_mfma_f32_16x16x32_bf16 v[48:51], v[236:239], v[88:91], v[48:51]
	v_mfma_f32_16x16x32_bf16 v[16:19], v[236:239], v[72:75], v[16:19]
	ds_read_b64 v[236:237], v76 offset:40960
	ds_read_b64 v[238:239], v77 offset:40960
	s_waitcnt lgkmcnt(14)
	v_mfma_f32_16x16x32_bf16 v[44:47], v[240:243], v[88:91], v[44:47]
	v_mfma_f32_16x16x32_bf16 v[12:15], v[240:243], v[72:75], v[12:15]
	ds_read_b64 v[240:241], v76 offset:43008
	ds_read_b64 v[242:243], v77 offset:43008
	s_waitcnt lgkmcnt(14)
	v_mfma_f32_16x16x32_bf16 v[40:43], v[244:247], v[88:91], v[40:43]
	v_mfma_f32_16x16x32_bf16 v[8:11], v[244:247], v[72:75], v[8:11]
	ds_read_b64 v[244:245], v76 offset:45056
	ds_read_b64 v[246:247], v77 offset:45056
	s_waitcnt lgkmcnt(14)
	v_mfma_f32_16x16x32_bf16 v[36:39], v[248:251], v[88:91], v[36:39]
	v_mfma_f32_16x16x32_bf16 v[4:7], v[248:251], v[72:75], v[4:7]
	ds_read_b64 v[248:249], v76 offset:47104
	ds_read_b64 v[250:251], v77 offset:47104
	s_waitcnt lgkmcnt(14)
	v_mfma_f32_16x16x32_bf16 v[64:67], v[220:223], v[84:87], v[64:67]
	v_mfma_f32_16x16x32_bf16 v[32:35], v[220:223], v[68:71], v[32:35]
	s_waitcnt lgkmcnt(12)
	v_mfma_f32_16x16x32_bf16 v[60:63], v[224:227], v[84:87], v[60:63]
	v_mfma_f32_16x16x32_bf16 v[28:31], v[224:227], v[68:71], v[28:31]
	s_waitcnt lgkmcnt(10)
	v_mfma_f32_16x16x32_bf16 v[56:59], v[228:231], v[84:87], v[56:59]
	v_mfma_f32_16x16x32_bf16 v[24:27], v[228:231], v[68:71], v[24:27]
	s_waitcnt lgkmcnt(8)
	v_mfma_f32_16x16x32_bf16 v[52:55], v[232:235], v[84:87], v[52:55]
	v_mfma_f32_16x16x32_bf16 v[20:23], v[232:235], v[68:71], v[20:23]
	s_waitcnt lgkmcnt(6)
	v_mfma_f32_16x16x32_bf16 v[48:51], v[236:239], v[84:87], v[48:51]
	v_mfma_f32_16x16x32_bf16 v[16:19], v[236:239], v[68:71], v[16:19]
	s_waitcnt lgkmcnt(4)
	v_mfma_f32_16x16x32_bf16 v[44:47], v[240:243], v[84:87], v[44:47]
	v_mfma_f32_16x16x32_bf16 v[12:15], v[240:243], v[68:71], v[12:15]
	s_waitcnt lgkmcnt(2)
	v_mfma_f32_16x16x32_bf16 v[40:43], v[244:247], v[84:87], v[40:43]
	v_mfma_f32_16x16x32_bf16 v[8:11], v[244:247], v[68:71], v[8:11]
	s_waitcnt lgkmcnt(0)
	v_mfma_f32_16x16x32_bf16 v[36:39], v[248:251], v[84:87], v[36:39]
	v_mfma_f32_16x16x32_bf16 v[4:7], v[248:251], v[68:71], v[4:7]
